# E2 + q|f lb preload + batched GEMM3 epilogue + GEMM2 hook load ring + batched GEMM2 epilogue (baseline K-loop waits)
# speedup vs baseline: 1.0008x; 1.0008x over previous
; #define PG8_STAGE(bufoff, gbase, voff) do { _Pragma("unroll") for (int _i = 0; _i < 2; ++_i) \
;         __builtin_amdgcn_global_load_lds((const unsigned*)((const char*)(gbase) + (voff)[_i]), (LAS unsigned*)(lds + (bufoff) + ldsw + _i * 8192), 16, 0, 0); } while (0)
; #define PG8_LDA(dst, b, h) do { _Pragma("unroll") for (int m = 0; m < 4; ++m) _Pragma("unroll") for (int k = 0; k < 2; ++k) dst[m][k] = *(const LAS bf16x8*)(lds + PG8_SA(b, h) + aoff + m * 2048 + k * 1024); } while (0)
; #define PG8_LDB(dst, b, h) do { _Pragma("unroll") for (int n = 0; n < 2; ++n) _Pragma("unroll") for (int k = 0; k < 2; ++k) dst[n][k] = *(const LAS bf16x8*)(lds + PG8_SB(b, h) + boff + n * 2048 + k * 1024); } while (0)
; #define PG8_MMA(ai, bj, At, Bt) do { __builtin_amdgcn_s_setprio(1); _Pragma("unroll") for (int m = 0; m < 4; ++m) _Pragma("unroll") for (int n = 0; n < 2; ++n) _Pragma("unroll") for (int k = 0; k < 2; ++k) \
;         acc[ai][bj][m][n] = __builtin_amdgcn_mfma_f32_16x16x32_bf16(Bt[n][k], At[m][k], acc[ai][bj][m][n], 0, 0, 0); __builtin_amdgcn_s_setprio(0); } while (0)
; #define PG8_WAIT_V(n) asm volatile("s_waitcnt vmcnt(" #n ")" ::: "memory")
; #define PG8_BAR __builtin_amdgcn_s_barrier()
; template <class Epi>
; __device__ __forceinline__ void gemm_phase(LAS unsigned char* lds, const Gemm g, const StaticOrder& S, const Epi& E) {
;     ...
;         for (int t = 0; t < nt; t += 2) {
;             const bool last = (t == nt - 2);
;             if constexpr (Epi::MIDHOOK) { if (t == nt / 2) { if (wr == 0) PG8_BAR; E.mid(acc, cur, wr, wc, fr, fq); if (wr == 1) PG8_BAR; } }
;             const char* a1 = cA + (size_t)(t + 1) * kstep;
;             const char* a2 = last ? nA : cA + (size_t)(t + 2) * kstep; const char* b2 = last ? nB : cB + (size_t)(t + 2) * kstep;
;             const char* a3 = a2 + kstep; const char* b3 = b2 + kstep;
;             PG8_LDB(B0, 0, 0); PG8_LDA(At, 0, 0); PG8_LDB(B1, 0, 1); PG8_STAGE(PG8_SA(1, 1), a1 + hstep, voffA);
;             PG8_WAIT_L(0); PG8_BAR; PG8_SCHED; PG8_MMA(0, 0, At, B0); PG8_MMA(0, 1, At, B1); PG8_SCHED; PG8_BAR; PG8_SCHED;
;             PG8_LDA(At, 0, 1); PG8_STAGE(PG8_SB(0, 0), b2, voffB); PG8_STAGE(PG8_SA(0, 0), a2, voffA); PG8_STAGE(PG8_SB(0, 1), b2 + hstep, voffB);
;             PG8_WAIT_V(6); PG8_WAIT_L(0); PG8_BAR; PG8_SCHED; PG8_MMA(1, 0, At, B0); PG8_MMA(1, 1, At, B1); PG8_SCHED; PG8_BAR; PG8_SCHED;
.LBB0_129:
	s_add_u32 s47, s66, 0xfff04000
	s_addc_u32 s51, s67, -1
	s_cmp_eq_u32 s35, 60
	s_cselect_b32 s53, s3, s51
	s_cselect_b32 s52, s5, s47
	s_cselect_b32 s59, s14, s34
	s_cselect_b32 s58, s26, s27
	v_lshl_add_u64 v[206:207], s[66:67], 0, v[128:129]
	s_add_i32 m0, s65, 0xc000
	ds_read_b128 v[134:137], v177
	ds_read_b128 v[138:141], v177 offset:1024
	ds_read_b128 v[142:145], v177 offset:2048
	ds_read_b128 v[146:149], v177 offset:3072
	ds_read_b128 v[150:153], v178
	ds_read_b128 v[154:157], v178 offset:1024
	ds_read_b128 v[158:161], v178 offset:2048
	ds_read_b128 v[162:165], v178 offset:3072
	ds_read_b128 v[166:169], v178 offset:4096
	ds_read_b128 v[170:173], v178 offset:5120
	ds_read_b128 v[182:185], v178 offset:6144
	ds_read_b128 v[186:189], v178 offset:7168
	ds_read_b128 v[190:193], v179
	ds_read_b128 v[194:197], v179 offset:1024
	ds_read_b128 v[198:201], v179 offset:2048
	ds_read_b128 v[202:205], v179 offset:3072
	global_load_lds_dwordx4 v[206:207], off
	v_lshl_add_u64 v[206:207], v[206:207], 0, s[8:9]
	s_add_i32 m0, s65, 0xe000
	s_nop 0
	global_load_lds_dwordx4 v[206:207], off
	s_waitcnt lgkmcnt(0)
	s_barrier
	s_setprio 1
	s_waitcnt lgkmcnt(0)
	v_mfma_f32_16x16x32_bf16 v[124:127], v[134:137], v[150:153], v[124:127]
	v_mfma_f32_16x16x32_bf16 v[116:119], v[142:145], v[150:153], v[116:119]
	v_mfma_f32_16x16x32_bf16 v[108:111], v[134:137], v[158:161], v[108:111]
	v_mfma_f32_16x16x32_bf16 v[100:103], v[142:145], v[158:161], v[100:103]
	v_mfma_f32_16x16x32_bf16 v[92:95], v[134:137], v[166:169], v[92:95]
	v_mfma_f32_16x16x32_bf16 v[84:87], v[142:145], v[166:169], v[84:87]
	v_mfma_f32_16x16x32_bf16 v[76:79], v[134:137], v[182:185], v[76:79]
	v_mfma_f32_16x16x32_bf16 v[68:71], v[142:145], v[182:185], v[68:71]
	v_mfma_f32_16x16x32_bf16 v[124:127], v[138:141], v[154:157], v[124:127]
	v_mfma_f32_16x16x32_bf16 v[116:119], v[146:149], v[154:157], v[116:119]
	v_mfma_f32_16x16x32_bf16 v[108:111], v[138:141], v[162:165], v[108:111]
	v_mfma_f32_16x16x32_bf16 v[100:103], v[146:149], v[162:165], v[100:103]
	v_mfma_f32_16x16x32_bf16 v[92:95], v[138:141], v[170:173], v[92:95]
	v_mfma_f32_16x16x32_bf16 v[84:87], v[146:149], v[170:173], v[84:87]
	v_mfma_f32_16x16x32_bf16 v[76:79], v[138:141], v[186:189], v[76:79]
	v_mfma_f32_16x16x32_bf16 v[68:71], v[146:149], v[186:189], v[68:71]
	s_setprio 0
	s_setprio 1
	v_mfma_f32_16x16x32_bf16 v[120:123], v[190:193], v[150:153], v[120:123]
	v_mfma_f32_16x16x32_bf16 v[112:115], v[198:201], v[150:153], v[112:115]
	v_mfma_f32_16x16x32_bf16 v[104:107], v[190:193], v[158:161], v[104:107]
	v_mfma_f32_16x16x32_bf16 v[96:99], v[198:201], v[158:161], v[96:99]
	v_mfma_f32_16x16x32_bf16 v[88:91], v[190:193], v[166:169], v[88:91]
	v_mfma_f32_16x16x32_bf16 v[80:83], v[198:201], v[166:169], v[80:83]
	v_mfma_f32_16x16x32_bf16 v[72:75], v[190:193], v[182:185], v[72:75]
	v_mfma_f32_16x16x32_bf16 v[64:67], v[198:201], v[182:185], v[64:67]
	v_mfma_f32_16x16x32_bf16 v[120:123], v[194:197], v[154:157], v[120:123]
	v_mfma_f32_16x16x32_bf16 v[112:115], v[202:205], v[154:157], v[112:115]
	v_mfma_f32_16x16x32_bf16 v[104:107], v[194:197], v[162:165], v[104:107]
	v_mfma_f32_16x16x32_bf16 v[96:99], v[202:205], v[162:165], v[96:99]
	v_mfma_f32_16x16x32_bf16 v[88:91], v[194:197], v[170:173], v[88:91]
	v_mfma_f32_16x16x32_bf16 v[80:83], v[202:205], v[170:173], v[80:83]
	v_mfma_f32_16x16x32_bf16 v[72:75], v[194:197], v[186:189], v[72:75]
	v_mfma_f32_16x16x32_bf16 v[64:67], v[202:205], v[186:189], v[64:67]
	s_setprio 0
	s_barrier
	s_add_i32 s47, s92, s75
	v_lshl_add_u64 v[206:207], s[58:59], 0, v[128:129]
	s_mov_b32 m0, s47
	ds_read_b128 v[150:153], v178 offset:16384
	ds_read_b128 v[154:157], v178 offset:17408
	ds_read_b128 v[158:161], v178 offset:18432
	ds_read_b128 v[162:165], v178 offset:19456
	ds_read_b128 v[166:169], v178 offset:20480
	ds_read_b128 v[170:173], v178 offset:21504
	ds_read_b128 v[182:185], v178 offset:22528
	ds_read_b128 v[186:189], v178 offset:23552
	global_load_lds_dwordx4 v[206:207], off
	v_lshl_add_u64 v[208:209], v[206:207], 0, s[8:9]
	s_add_i32 m0, s47, 0x2000
	s_add_i32 s47, s93, s75
	global_load_lds_dwordx4 v[208:209], off
	v_lshl_add_u64 v[208:209], s[52:53], 0, v[128:129]
	s_mov_b32 m0, s65
	v_lshl_add_u64 v[212:213], v[208:209], 0, s[8:9]
	global_load_lds_dwordx4 v[208:209], off
	s_mov_b32 m0, s76
	s_nop 0
	global_load_lds_dwordx4 v[212:213], off
	v_lshl_add_u64 v[212:213], v[206:207], 0, s[10:11]
	s_mov_b32 m0, s47
	s_nop 0
	global_load_lds_dwordx4 v[212:213], off
	v_lshl_add_u64 v[212:213], v[206:207], 0, s[12:13]
	s_add_i32 m0, s47, 0x2000
	s_nop 0
	global_load_lds_dwordx4 v[212:213], off
	s_waitcnt vmcnt(6)
	s_waitcnt lgkmcnt(0)
	s_barrier
; #define PG8_STAGE(bufoff, gbase, voff) do { _Pragma("unroll") for (int _i = 0; _i < 2; ++_i) \
;         __builtin_amdgcn_global_load_lds((const unsigned*)((const char*)(gbase) + (voff)[_i]), (LAS unsigned*)(lds + (bufoff) + ldsw + _i * 8192), 16, 0, 0); } while (0)
; #define PG8_LDA(dst, b, h) do { _Pragma("unroll") for (int m = 0; m < 4; ++m) _Pragma("unroll") for (int k = 0; k < 2; ++k) dst[m][k] = *(const LAS bf16x8*)(lds + PG8_SA(b, h) + aoff + m * 2048 + k * 1024); } while (0)
; #define PG8_LDB(dst, b, h) do { _Pragma("unroll") for (int n = 0; n < 2; ++n) _Pragma("unroll") for (int k = 0; k < 2; ++k) dst[n][k] = *(const LAS bf16x8*)(lds + PG8_SB(b, h) + boff + n * 2048 + k * 1024); } while (0)
; #define PG8_MMA(ai, bj, At, Bt) do { __builtin_amdgcn_s_setprio(1); _Pragma("unroll") for (int m = 0; m < 4; ++m) _Pragma("unroll") for (int n = 0; n < 2; ++n) _Pragma("unroll") for (int k = 0; k < 2; ++k) \
;         acc[ai][bj][m][n] = __builtin_amdgcn_mfma_f32_16x16x32_bf16(Bt[n][k], At[m][k], acc[ai][bj][m][n], 0, 0, 0); __builtin_amdgcn_s_setprio(0); } while (0)
; #define PG8_WAIT_V(n) asm volatile("s_waitcnt vmcnt(" #n ")" ::: "memory")
; #define PG8_WAIT_L(n) asm volatile("s_waitcnt lgkmcnt(" #n ")" ::: "memory")
; #define PG8_BAR __builtin_amdgcn_s_barrier()
; #define PG8_SCHED __builtin_amdgcn_sched_barrier(0)
; template <class Epi>
; __device__ __forceinline__ void gemm_phase(LAS unsigned char* lds, const Gemm g, const StaticOrder& S, const Epi& E) {
;     ...
;             PG8_WAIT_L(0); PG8_BAR; PG8_SCHED; PG8_MMA(0, 0, At, B0); PG8_MMA(0, 1, At, B1); PG8_SCHED; PG8_BAR; PG8_SCHED;
;             PG8_LDA(At, 0, 1); PG8_STAGE(PG8_SB(0, 0), b2, voffB); PG8_STAGE(PG8_SA(0, 0), a2, voffA); PG8_STAGE(PG8_SB(0, 1), b2 + hstep, voffB);
;             PG8_WAIT_V(6); PG8_WAIT_L(0); PG8_BAR; PG8_SCHED; PG8_MMA(1, 0, At, B0); PG8_MMA(1, 1, At, B1); PG8_SCHED; PG8_BAR; PG8_SCHED;
;             PG8_LDB(B0, 1, 0); PG8_LDA(At, 1, 0); PG8_LDB(B1, 1, 1); PG8_STAGE(PG8_SA(0, 1), a2 + hstep, voffA);
;             PG8_WAIT_L(0); PG8_BAR; PG8_SCHED; PG8_MMA(0, 0, At, B0); PG8_MMA(0, 1, At, B1); PG8_SCHED; PG8_BAR; PG8_SCHED;
	s_setprio 1
	s_waitcnt lgkmcnt(0)
	v_mfma_f32_16x16x32_bf16 v[60:63], v[134:137], v[150:153], v[60:63]
	v_mfma_f32_16x16x32_bf16 v[52:55], v[142:145], v[150:153], v[52:55]
	v_mfma_f32_16x16x32_bf16 v[44:47], v[134:137], v[158:161], v[44:47]
	v_mfma_f32_16x16x32_bf16 v[36:39], v[142:145], v[158:161], v[36:39]
	v_mfma_f32_16x16x32_bf16 v[28:31], v[134:137], v[166:169], v[28:31]
	v_mfma_f32_16x16x32_bf16 v[20:23], v[142:145], v[166:169], v[20:23]
	v_mfma_f32_16x16x32_bf16 v[12:15], v[134:137], v[182:185], v[12:15]
	v_mfma_f32_16x16x32_bf16 v[4:7], v[142:145], v[182:185], v[4:7]
	v_mfma_f32_16x16x32_bf16 v[60:63], v[138:141], v[154:157], v[60:63]
	v_mfma_f32_16x16x32_bf16 v[52:55], v[146:149], v[154:157], v[52:55]
	v_mfma_f32_16x16x32_bf16 v[44:47], v[138:141], v[162:165], v[44:47]
	v_mfma_f32_16x16x32_bf16 v[36:39], v[146:149], v[162:165], v[36:39]
	v_mfma_f32_16x16x32_bf16 v[28:31], v[138:141], v[170:173], v[28:31]
	v_mfma_f32_16x16x32_bf16 v[20:23], v[146:149], v[170:173], v[20:23]
	v_mfma_f32_16x16x32_bf16 v[12:15], v[138:141], v[186:189], v[12:15]
	v_mfma_f32_16x16x32_bf16 v[4:7], v[146:149], v[186:189], v[4:7]
	s_setprio 0
	s_setprio 1
	v_mfma_f32_16x16x32_bf16 v[56:59], v[190:193], v[150:153], v[56:59]
	v_mfma_f32_16x16x32_bf16 v[48:51], v[198:201], v[150:153], v[48:51]
	v_mfma_f32_16x16x32_bf16 v[40:43], v[190:193], v[158:161], v[40:43]
	v_mfma_f32_16x16x32_bf16 v[32:35], v[198:201], v[158:161], v[32:35]
	v_mfma_f32_16x16x32_bf16 v[24:27], v[190:193], v[166:169], v[24:27]
	v_mfma_f32_16x16x32_bf16 v[16:19], v[198:201], v[166:169], v[16:19]
	v_mfma_f32_16x16x32_bf16 v[8:11], v[190:193], v[182:185], v[8:11]
	v_mfma_f32_16x16x32_bf16 v[0:3], v[198:201], v[182:185], v[0:3]
	v_mfma_f32_16x16x32_bf16 v[56:59], v[194:197], v[154:157], v[56:59]
	v_mfma_f32_16x16x32_bf16 v[48:51], v[202:205], v[154:157], v[48:51]
	v_mfma_f32_16x16x32_bf16 v[40:43], v[194:197], v[162:165], v[40:43]
	v_mfma_f32_16x16x32_bf16 v[32:35], v[202:205], v[162:165], v[32:35]
	v_mfma_f32_16x16x32_bf16 v[24:27], v[194:197], v[170:173], v[24:27]
	v_mfma_f32_16x16x32_bf16 v[16:19], v[202:205], v[170:173], v[16:19]
	v_mfma_f32_16x16x32_bf16 v[8:11], v[194:197], v[186:189], v[8:11]
	v_mfma_f32_16x16x32_bf16 v[0:3], v[202:205], v[186:189], v[0:3]
	s_setprio 0
	s_barrier
	s_add_i32 s47, 0, 0x18000
	s_add_i32 s51, 0, 0x1c000
	s_mov_b32 m0, s77
	v_add_u32_e32 v146, s47, v176
	v_add_u32_e32 v181, s51, v176
	v_lshl_add_u64 v[212:213], v[208:209], 0, s[10:11]
	ds_read_b128 v[134:137], v146
	ds_read_b128 v[138:141], v146 offset:1024
	ds_read_b128 v[142:145], v146 offset:2048
	ds_read_b128 v[146:149], v146 offset:3072
	ds_read_b128 v[150:153], v178 offset:32768
	ds_read_b128 v[154:157], v178 offset:33792
	ds_read_b128 v[158:161], v178 offset:34816
	ds_read_b128 v[162:165], v178 offset:35840
	ds_read_b128 v[166:169], v178 offset:36864
	ds_read_b128 v[170:173], v178 offset:37888
	ds_read_b128 v[182:185], v178 offset:38912
	ds_read_b128 v[186:189], v178 offset:39936
	ds_read_b128 v[190:193], v181
	ds_read_b128 v[194:197], v181 offset:1024
	ds_read_b128 v[198:201], v181 offset:2048
	ds_read_b128 v[202:205], v181 offset:3072
	global_load_lds_dwordx4 v[212:213], off
	v_lshl_add_u64 v[212:213], v[208:209], 0, s[12:13]
	s_mov_b32 m0, s78
	s_nop 0
	global_load_lds_dwordx4 v[212:213], off
	s_waitcnt lgkmcnt(0)
	s_barrier
	s_setprio 1
	s_waitcnt lgkmcnt(0)
	v_mfma_f32_16x16x32_bf16 v[124:127], v[134:137], v[150:153], v[124:127]
	v_mfma_f32_16x16x32_bf16 v[116:119], v[142:145], v[150:153], v[116:119]
	v_mfma_f32_16x16x32_bf16 v[108:111], v[134:137], v[158:161], v[108:111]
	v_mfma_f32_16x16x32_bf16 v[100:103], v[142:145], v[158:161], v[100:103]
	v_mfma_f32_16x16x32_bf16 v[92:95], v[134:137], v[166:169], v[92:95]
	v_mfma_f32_16x16x32_bf16 v[84:87], v[142:145], v[166:169], v[84:87]
	v_mfma_f32_16x16x32_bf16 v[76:79], v[134:137], v[182:185], v[76:79]
	v_mfma_f32_16x16x32_bf16 v[68:71], v[142:145], v[182:185], v[68:71]
	v_mfma_f32_16x16x32_bf16 v[124:127], v[138:141], v[154:157], v[124:127]
	v_mfma_f32_16x16x32_bf16 v[116:119], v[146:149], v[154:157], v[116:119]
	v_mfma_f32_16x16x32_bf16 v[108:111], v[138:141], v[162:165], v[108:111]
	v_mfma_f32_16x16x32_bf16 v[100:103], v[146:149], v[162:165], v[100:103]
	v_mfma_f32_16x16x32_bf16 v[92:95], v[138:141], v[170:173], v[92:95]
	v_mfma_f32_16x16x32_bf16 v[84:87], v[146:149], v[170:173], v[84:87]
	v_mfma_f32_16x16x32_bf16 v[76:79], v[138:141], v[186:189], v[76:79]
	v_mfma_f32_16x16x32_bf16 v[68:71], v[146:149], v[186:189], v[68:71]
	s_setprio 0
	s_setprio 1
	v_mfma_f32_16x16x32_bf16 v[120:123], v[190:193], v[150:153], v[120:123]
	v_mfma_f32_16x16x32_bf16 v[112:115], v[198:201], v[150:153], v[112:115]
	v_mfma_f32_16x16x32_bf16 v[104:107], v[190:193], v[158:161], v[104:107]
	v_mfma_f32_16x16x32_bf16 v[96:99], v[198:201], v[158:161], v[96:99]
	v_mfma_f32_16x16x32_bf16 v[88:91], v[190:193], v[166:169], v[88:91]
	v_mfma_f32_16x16x32_bf16 v[80:83], v[198:201], v[166:169], v[80:83]
	v_mfma_f32_16x16x32_bf16 v[72:75], v[190:193], v[182:185], v[72:75]
	v_mfma_f32_16x16x32_bf16 v[64:67], v[198:201], v[182:185], v[64:67]
	v_mfma_f32_16x16x32_bf16 v[120:123], v[194:197], v[154:157], v[120:123]
	v_mfma_f32_16x16x32_bf16 v[112:115], v[202:205], v[154:157], v[112:115]
	v_mfma_f32_16x16x32_bf16 v[104:107], v[194:197], v[162:165], v[104:107]
	v_mfma_f32_16x16x32_bf16 v[96:99], v[202:205], v[162:165], v[96:99]
	v_mfma_f32_16x16x32_bf16 v[88:91], v[194:197], v[170:173], v[88:91]
	v_mfma_f32_16x16x32_bf16 v[80:83], v[202:205], v[170:173], v[80:83]
	v_mfma_f32_16x16x32_bf16 v[72:75], v[194:197], v[186:189], v[72:75]
	v_mfma_f32_16x16x32_bf16 v[64:67], v[202:205], v[186:189], v[64:67]
	s_setprio 0
	s_barrier
; #define PG8_STAGE(bufoff, gbase, voff) do { _Pragma("unroll") for (int _i = 0; _i < 2; ++_i) \
;         __builtin_amdgcn_global_load_lds((const unsigned*)((const char*)(gbase) + (voff)[_i]), (LAS unsigned*)(lds + (bufoff) + ldsw + _i * 8192), 16, 0, 0); } while (0)
; #define PG8_LDA(dst, b, h) do { _Pragma("unroll") for (int m = 0; m < 4; ++m) _Pragma("unroll") for (int k = 0; k < 2; ++k) dst[m][k] = *(const LAS bf16x8*)(lds + PG8_SA(b, h) + aoff + m * 2048 + k * 1024); } while (0)
; #define PG8_MMA(ai, bj, At, Bt) do { __builtin_amdgcn_s_setprio(1); _Pragma("unroll") for (int m = 0; m < 4; ++m) _Pragma("unroll") for (int n = 0; n < 2; ++n) _Pragma("unroll") for (int k = 0; k < 2; ++k) \
;         acc[ai][bj][m][n] = __builtin_amdgcn_mfma_f32_16x16x32_bf16(Bt[n][k], At[m][k], acc[ai][bj][m][n], 0, 0, 0); __builtin_amdgcn_s_setprio(0); } while (0)
; #define PG8_WAIT_V(n) asm volatile("s_waitcnt vmcnt(" #n ")" ::: "memory")
; #define PG8_WAIT_L(n) asm volatile("s_waitcnt lgkmcnt(" #n ")" ::: "memory")
; #define PG8_BAR __builtin_amdgcn_s_barrier()
; #define PG8_SCHED __builtin_amdgcn_sched_barrier(0)
; template <class Epi>
; __device__ __forceinline__ void gemm_phase(LAS unsigned char* lds, const Gemm g, const StaticOrder& S, const Epi& E) {
;     ...
;             PG8_LDA(At, 1, 1); PG8_STAGE(PG8_SB(1, 0), b3, voffB); PG8_STAGE(PG8_SA(1, 0), a3, voffA); PG8_STAGE(PG8_SB(1, 1), b3 + hstep, voffB);
;             PG8_WAIT_V(6); PG8_WAIT_L(0); PG8_BAR; PG8_SCHED; PG8_MMA(1, 0, At, B0); PG8_MMA(1, 1, At, B1); PG8_SCHED; PG8_BAR; PG8_SCHED;
;         }
;         PG8_SCHED;
;         if (wr == 0) PG8_BAR;
	s_add_i32 s47, s47, s75
	v_lshl_add_u64 v[212:213], v[206:207], 0, s[18:19]
	s_mov_b32 m0, s47
	ds_read_b128 v[150:153], v178 offset:49152
	ds_read_b128 v[154:157], v178 offset:50176
	ds_read_b128 v[158:161], v178 offset:51200
	ds_read_b128 v[162:165], v178 offset:52224
	ds_read_b128 v[166:169], v178 offset:53248
	ds_read_b128 v[170:173], v178 offset:54272
	ds_read_b128 v[182:185], v178 offset:55296
	ds_read_b128 v[186:189], v178 offset:56320
	global_load_lds_dwordx4 v[212:213], off
	v_lshl_add_u64 v[212:213], v[206:207], 0, s[20:21]
	s_add_i32 m0, s47, 0x2000
	s_add_i32 s47, s51, s75
	global_load_lds_dwordx4 v[212:213], off
	v_lshl_add_u64 v[212:213], v[208:209], 0, s[18:19]
	s_mov_b32 m0, s80
	v_lshl_add_u64 v[208:209], v[208:209], 0, s[20:21]
	global_load_lds_dwordx4 v[212:213], off
	s_mov_b32 m0, s81
	s_nop 0
	global_load_lds_dwordx4 v[208:209], off
	v_lshl_add_u64 v[208:209], v[206:207], 0, s[22:23]
	s_mov_b32 m0, s47
	v_lshl_add_u64 v[206:207], v[206:207], 0, s[24:25]
	global_load_lds_dwordx4 v[208:209], off
	s_add_i32 m0, s47, 0x2000
	s_nop 0
	global_load_lds_dwordx4 v[206:207], off
	s_waitcnt vmcnt(6)
	s_waitcnt lgkmcnt(0)
	s_barrier
	s_setprio 1
	s_waitcnt lgkmcnt(0)
	v_mfma_f32_16x16x32_bf16 v[60:63], v[134:137], v[150:153], v[60:63]
	v_mfma_f32_16x16x32_bf16 v[52:55], v[142:145], v[150:153], v[52:55]
	v_mfma_f32_16x16x32_bf16 v[44:47], v[134:137], v[158:161], v[44:47]
	v_mfma_f32_16x16x32_bf16 v[36:39], v[142:145], v[158:161], v[36:39]
	v_mfma_f32_16x16x32_bf16 v[28:31], v[134:137], v[166:169], v[28:31]
	v_mfma_f32_16x16x32_bf16 v[20:23], v[142:145], v[166:169], v[20:23]
	v_mfma_f32_16x16x32_bf16 v[12:15], v[134:137], v[182:185], v[12:15]
	v_mfma_f32_16x16x32_bf16 v[4:7], v[142:145], v[182:185], v[4:7]
	v_mfma_f32_16x16x32_bf16 v[60:63], v[138:141], v[154:157], v[60:63]
	v_mfma_f32_16x16x32_bf16 v[52:55], v[146:149], v[154:157], v[52:55]
	v_mfma_f32_16x16x32_bf16 v[44:47], v[138:141], v[162:165], v[44:47]
	v_mfma_f32_16x16x32_bf16 v[36:39], v[146:149], v[162:165], v[36:39]
	v_mfma_f32_16x16x32_bf16 v[28:31], v[138:141], v[170:173], v[28:31]
	v_mfma_f32_16x16x32_bf16 v[20:23], v[146:149], v[170:173], v[20:23]
	v_mfma_f32_16x16x32_bf16 v[12:15], v[138:141], v[186:189], v[12:15]
	v_mfma_f32_16x16x32_bf16 v[4:7], v[146:149], v[186:189], v[4:7]
	s_setprio 0
	s_setprio 1
	v_mfma_f32_16x16x32_bf16 v[56:59], v[190:193], v[150:153], v[56:59]
	v_mfma_f32_16x16x32_bf16 v[48:51], v[198:201], v[150:153], v[48:51]
	v_mfma_f32_16x16x32_bf16 v[40:43], v[190:193], v[158:161], v[40:43]
	v_mfma_f32_16x16x32_bf16 v[32:35], v[198:201], v[158:161], v[32:35]
	v_mfma_f32_16x16x32_bf16 v[24:27], v[190:193], v[166:169], v[24:27]
	v_mfma_f32_16x16x32_bf16 v[16:19], v[198:201], v[166:169], v[16:19]
	v_mfma_f32_16x16x32_bf16 v[8:11], v[190:193], v[182:185], v[8:11]
	v_mfma_f32_16x16x32_bf16 v[0:3], v[198:201], v[182:185], v[0:3]
	v_mfma_f32_16x16x32_bf16 v[56:59], v[194:197], v[154:157], v[56:59]
	v_mfma_f32_16x16x32_bf16 v[48:51], v[202:205], v[154:157], v[48:51]
	v_mfma_f32_16x16x32_bf16 v[40:43], v[194:197], v[162:165], v[40:43]
	v_mfma_f32_16x16x32_bf16 v[32:35], v[202:205], v[162:165], v[32:35]
	v_mfma_f32_16x16x32_bf16 v[24:27], v[194:197], v[170:173], v[24:27]
	v_mfma_f32_16x16x32_bf16 v[16:19], v[202:205], v[170:173], v[16:19]
	v_mfma_f32_16x16x32_bf16 v[8:11], v[194:197], v[186:189], v[8:11]
	v_mfma_f32_16x16x32_bf16 v[0:3], v[202:205], v[186:189], v[0:3]
	s_setprio 0
	s_barrier
	s_add_i32 s35, s35, 2
	s_add_u32 s66, s66, 0x8000
	s_addc_u32 s67, s67, 0
	s_add_u32 s27, s27, 0x8000
	s_addc_u32 s34, s34, 0
	s_cmp_gt_u32 s35, 61
	s_cbranch_scc0 .LBB0_129
	s_and_b64 vcc, exec, s[38:39]
	s_cbranch_vccz .LBB0_132
	s_barrier
